# v021 + final RMSNorm phase (P14): 4 rows per wave iteration with all their loads in flight together (was one row at a time with vmcnt(0) per row); same arithmetic
# baseline (speedup 1.0000x reference)
; __device__ __forceinline__ float bflo(unsigned u) { return __uint_as_float(u << 16); }
; __device__ __forceinline__ float bfhi(unsigned u) { return __uint_as_float(u & 0xffff0000u); }
; __device__ __forceinline__ void rms_row_final(const bf16* __restrict__ xrow, const float* __restrict__ srow, float* __restrict__ orow, const float* __restrict__ gain, int lane) {
;     const f32x4 s0 = *(const f32x4*)srow, s1 = *(const f32x4*)(srow + 4), s2 = *(const f32x4*)(srow + 8), s3 = *(const f32x4*)(srow + 12);
;     const float ss = (((s0[0] + s0[1]) + (s0[2] + s0[3])) + ((s1[0] + s1[1]) + (s1[2] + s1[3]))) + (((s2[0] + s2[1]) + (s2[2] + s2[3])) + ((s3[0] + s3[1]) + (s3[2] + s3[3])));
;     const float rstd = __builtin_amdgcn_rsqf(ss * (1.f / D) + 1e-6f);
;     const v2u* xr = (const v2u*)xrow + lane; const f32x4* gr = (const f32x4*)gain + lane; f32x4* o = (f32x4*)orow + lane;
; #pragma unroll
;     for (int j = 0; j < 4; ++j) { const v2u v = __builtin_nontemporal_load(xr + 64 * j); const f32x4 g4 = gr[64 * j];
;         const f32x4 r4 = {bflo(v.x) * rstd * g4[0], bfhi(v.x) * rstd * g4[1], bflo(v.y) * rstd * g4[2], bfhi(v.y) * rstd * g4[3]}; __builtin_nontemporal_store(r4, o + 64 * j); }
; }
; __global__ void __launch_bounds__(NTHREADS, 2) trunk_fwd(Args args) {
;     ...
;     if (IN(14)) for (int m = gw; m < M; m += NGW) rms_row_final(XB + (size_t)m * D, slots + (size_t)m * 16, out + (size_t)m * D, final_norm, lane);
.Lp14_group:
	s_mul_i32 s14, s20, 3
	s_add_i32 s14, s14, s12
	s_cmp_lt_i32 s14, 0x8000
	s_cbranch_scc0 .LBB0_1275
	s_add_u32 s8, s82, s2
	v_lshl_add_u64 v[60:61], s[82:83], 0, v[18:19]
	s_addc_u32 s9, s83, s3
	v_add_co_u32_e32 v76, vcc, s10, v60
	s_add_i32 s12, s12, s20
	s_nop 0
	v_addc_co_u32_e32 v77, vcc, 0, v61, vcc
	global_load_dwordx4 v[60:63], v17, s[8:9]
	global_load_dwordx4 v[64:67], v17, s[8:9] offset:32
	global_load_dwordx4 v[68:71], v17, s[8:9] offset:16
	global_load_dwordx4 v[72:75], v17, s[8:9] offset:48
	global_load_dwordx2 v[78:79], v[76:77], off nt
	global_load_dwordx2 v[80:81], v[76:77], off offset:512 nt
	global_load_dwordx2 v[82:83], v[76:77], off offset:1024 nt
	global_load_dwordx2 v[84:85], v[76:77], off offset:1536 nt
	s_add_u32 s2, s2, s4
	s_addc_u32 s3, s3, s5
	v_lshl_add_u64 v[18:19], v[18:19], 0, s[0:1]
	s_add_u32 s8, s82, s2
	v_lshl_add_u64 v[100:101], s[82:83], 0, v[18:19]
	s_addc_u32 s9, s83, s3
	v_add_co_u32_e32 v116, vcc, s10, v100
	s_add_i32 s12, s12, s20
	s_nop 0
	v_addc_co_u32_e32 v117, vcc, 0, v101, vcc
	global_load_dwordx4 v[100:103], v17, s[8:9]
	global_load_dwordx4 v[104:107], v17, s[8:9] offset:32
	global_load_dwordx4 v[108:111], v17, s[8:9] offset:16
	global_load_dwordx4 v[112:115], v17, s[8:9] offset:48
	global_load_dwordx2 v[118:119], v[116:117], off nt
	global_load_dwordx2 v[120:121], v[116:117], off offset:512 nt
	global_load_dwordx2 v[122:123], v[116:117], off offset:1024 nt
	global_load_dwordx2 v[124:125], v[116:117], off offset:1536 nt
	s_add_u32 s2, s2, s4
	s_addc_u32 s3, s3, s5
	v_lshl_add_u64 v[18:19], v[18:19], 0, s[0:1]
	s_add_u32 s8, s82, s2
	v_lshl_add_u64 v[160:161], s[82:83], 0, v[18:19]
	s_addc_u32 s9, s83, s3
	v_add_co_u32_e32 v176, vcc, s10, v160
	s_add_i32 s12, s12, s20
	s_nop 0
	v_addc_co_u32_e32 v177, vcc, 0, v161, vcc
	global_load_dwordx4 v[160:163], v17, s[8:9]
	global_load_dwordx4 v[164:167], v17, s[8:9] offset:32
	global_load_dwordx4 v[168:171], v17, s[8:9] offset:16
	global_load_dwordx4 v[172:175], v17, s[8:9] offset:48
	global_load_dwordx2 v[178:179], v[176:177], off nt
	global_load_dwordx2 v[180:181], v[176:177], off offset:512 nt
	global_load_dwordx2 v[182:183], v[176:177], off offset:1024 nt
	global_load_dwordx2 v[184:185], v[176:177], off offset:1536 nt
	s_add_u32 s2, s2, s4
	s_addc_u32 s3, s3, s5
	v_lshl_add_u64 v[18:19], v[18:19], 0, s[0:1]
	s_add_u32 s8, s82, s2
	v_lshl_add_u64 v[200:201], s[82:83], 0, v[18:19]
	s_addc_u32 s9, s83, s3
	v_add_co_u32_e32 v216, vcc, s10, v200
	s_add_i32 s12, s12, s20
	s_nop 0
	v_addc_co_u32_e32 v217, vcc, 0, v201, vcc
	global_load_dwordx4 v[200:203], v17, s[8:9]
	global_load_dwordx4 v[204:207], v17, s[8:9] offset:32
	global_load_dwordx4 v[208:211], v17, s[8:9] offset:16
	global_load_dwordx4 v[212:215], v17, s[8:9] offset:48
	global_load_dwordx2 v[218:219], v[216:217], off nt
	global_load_dwordx2 v[220:221], v[216:217], off offset:512 nt
	global_load_dwordx2 v[222:223], v[216:217], off offset:1024 nt
	global_load_dwordx2 v[224:225], v[216:217], off offset:1536 nt
	s_add_u32 s2, s2, s4
	s_addc_u32 s3, s3, s5
	v_lshl_add_u64 v[18:19], v[18:19], 0, s[0:1]
	s_waitcnt vmcnt(24)
	v_mov_b32_e32 v76, v60
	v_mov_b32_e32 v77, v64
	v_mov_b32_e32 v64, v61
	v_mov_b32_e32 v60, v62
	v_mov_b32_e32 v61, v66
	v_mov_b32_e32 v66, v63
	v_mov_b32_e32 v62, v68
	v_mov_b32_e32 v63, v72
	v_mov_b32_e32 v72, v69
	v_mov_b32_e32 v68, v70
	v_mov_b32_e32 v69, v74
	v_mov_b32_e32 v74, v71
	v_pk_add_f32 v[64:65], v[76:77], v[64:65]
	v_pk_add_f32 v[60:61], v[60:61], v[66:67]
	v_pk_add_f32 v[62:63], v[62:63], v[72:73]
	v_pk_add_f32 v[66:67], v[68:69], v[74:75]
	v_pk_add_f32 v[60:61], v[64:65], v[60:61]
	v_pk_add_f32 v[62:63], v[62:63], v[66:67]
	v_lshlrev_b32_e32 v70, 16, v78
	v_pk_add_f32 v[60:61], v[60:61], v[62:63]
	v_and_b32_e32 v71, 0xffff0000, v78
	v_add_f32_e32 v60, v60, v61
	v_fmamk_f32 v60, v60, 0x3a800000, v16
	v_rsq_f32_e32 v60, v60
	v_lshlrev_b32_e32 v78, 16, v79
	v_and_b32_e32 v79, 0xffff0000, v79
	v_lshlrev_b32_e32 v86, 16, v80
	v_and_b32_e32 v87, 0xffff0000, v80
	v_lshlrev_b32_e32 v80, 16, v81
	v_and_b32_e32 v81, 0xffff0000, v81
	v_lshlrev_b32_e32 v88, 16, v82
	v_and_b32_e32 v89, 0xffff0000, v82
	v_lshlrev_b32_e32 v82, 16, v83
	v_and_b32_e32 v83, 0xffff0000, v83
	v_lshlrev_b32_e32 v90, 16, v84
	v_and_b32_e32 v91, 0xffff0000, v84
	v_lshlrev_b32_e32 v84, 16, v85
	v_and_b32_e32 v85, 0xffff0000, v85
	v_pk_mul_f32 v[62:63], v[60:61], v[70:71] op_sel_hi:[0,1]
	v_pk_mul_f32 v[64:65], v[60:61], v[78:79] op_sel_hi:[0,1]
	v_pk_mul_f32 v[66:67], v[60:61], v[86:87] op_sel_hi:[0,1]
	v_pk_mul_f32 v[68:69], v[60:61], v[80:81] op_sel_hi:[0,1]
	v_pk_mul_f32 v[70:71], v[60:61], v[88:89] op_sel_hi:[0,1]
	v_pk_mul_f32 v[72:73], v[60:61], v[82:83] op_sel_hi:[0,1]
	v_pk_mul_f32 v[74:75], v[60:61], v[90:91] op_sel_hi:[0,1]
	v_pk_mul_f32 v[76:77], v[60:61], v[84:85] op_sel_hi:[0,1]
	v_pk_mul_f32 v[60:61], v[0:1], v[62:63]
	v_pk_mul_f32 v[62:63], v[2:3], v[64:65]
	v_pk_mul_f32 v[64:65], v[4:5], v[66:67]
	v_pk_mul_f32 v[66:67], v[6:7], v[68:69]
	v_pk_mul_f32 v[68:69], v[8:9], v[70:71]
	v_pk_mul_f32 v[70:71], v[10:11], v[72:73]
	v_pk_mul_f32 v[72:73], v[12:13], v[74:75]
	v_pk_mul_f32 v[74:75], v[14:15], v[76:77]
	global_store_dwordx4 v[20:21], v[60:63], off offset:-2048 nt
	global_store_dwordx4 v[20:21], v[64:67], off offset:-1024 nt
	global_store_dwordx4 v[20:21], v[68:71], off nt
	global_store_dwordx4 v[20:21], v[72:75], off offset:1024 nt
	v_lshl_add_u64 v[20:21], v[20:21], 0, s[6:7]
	s_waitcnt vmcnt(20)
; __device__ __forceinline__ float bflo(unsigned u) { return __uint_as_float(u << 16); }
; __device__ __forceinline__ float bfhi(unsigned u) { return __uint_as_float(u & 0xffff0000u); }
; __device__ __forceinline__ void rms_row_final(const bf16* __restrict__ xrow, const float* __restrict__ srow, float* __restrict__ orow, const float* __restrict__ gain, int lane) {
;     const f32x4 s0 = *(const f32x4*)srow, s1 = *(const f32x4*)(srow + 4), s2 = *(const f32x4*)(srow + 8), s3 = *(const f32x4*)(srow + 12);
;     const float ss = (((s0[0] + s0[1]) + (s0[2] + s0[3])) + ((s1[0] + s1[1]) + (s1[2] + s1[3]))) + (((s2[0] + s2[1]) + (s2[2] + s2[3])) + ((s3[0] + s3[1]) + (s3[2] + s3[3])));
;     const float rstd = __builtin_amdgcn_rsqf(ss * (1.f / D) + 1e-6f);
;     const v2u* xr = (const v2u*)xrow + lane; const f32x4* gr = (const f32x4*)gain + lane; f32x4* o = (f32x4*)orow + lane;
; #pragma unroll
;     for (int j = 0; j < 4; ++j) { const v2u v = __builtin_nontemporal_load(xr + 64 * j); const f32x4 g4 = gr[64 * j];
;         const f32x4 r4 = {bflo(v.x) * rstd * g4[0], bfhi(v.x) * rstd * g4[1], bflo(v.y) * rstd * g4[2], bfhi(v.y) * rstd * g4[3]}; __builtin_nontemporal_store(r4, o + 64 * j); }
; }
	v_mov_b32_e32 v116, v100
	v_mov_b32_e32 v117, v104
	v_mov_b32_e32 v104, v101
	v_mov_b32_e32 v100, v102
	v_mov_b32_e32 v101, v106
	v_mov_b32_e32 v106, v103
	v_mov_b32_e32 v102, v108
	v_mov_b32_e32 v103, v112
	v_mov_b32_e32 v112, v109
	v_mov_b32_e32 v108, v110
	v_mov_b32_e32 v109, v114
	v_mov_b32_e32 v114, v111
	v_pk_add_f32 v[104:105], v[116:117], v[104:105]
	v_pk_add_f32 v[100:101], v[100:101], v[106:107]
	v_pk_add_f32 v[102:103], v[102:103], v[112:113]
	v_pk_add_f32 v[106:107], v[108:109], v[114:115]
	v_pk_add_f32 v[100:101], v[104:105], v[100:101]
	v_pk_add_f32 v[102:103], v[102:103], v[106:107]
	v_lshlrev_b32_e32 v110, 16, v118
	v_pk_add_f32 v[100:101], v[100:101], v[102:103]
	v_and_b32_e32 v111, 0xffff0000, v118
	v_add_f32_e32 v100, v100, v101
	v_fmamk_f32 v100, v100, 0x3a800000, v16
	v_rsq_f32_e32 v100, v100
	v_lshlrev_b32_e32 v118, 16, v119
	v_and_b32_e32 v119, 0xffff0000, v119
	v_lshlrev_b32_e32 v126, 16, v120
	v_and_b32_e32 v127, 0xffff0000, v120
	v_lshlrev_b32_e32 v120, 16, v121
	v_and_b32_e32 v121, 0xffff0000, v121
	v_lshlrev_b32_e32 v128, 16, v122
	v_and_b32_e32 v129, 0xffff0000, v122
	v_lshlrev_b32_e32 v122, 16, v123
	v_and_b32_e32 v123, 0xffff0000, v123
	v_lshlrev_b32_e32 v130, 16, v124
	v_and_b32_e32 v131, 0xffff0000, v124
	v_lshlrev_b32_e32 v124, 16, v125
	v_and_b32_e32 v125, 0xffff0000, v125
	v_pk_mul_f32 v[102:103], v[100:101], v[110:111] op_sel_hi:[0,1]
	v_pk_mul_f32 v[104:105], v[100:101], v[118:119] op_sel_hi:[0,1]
	v_pk_mul_f32 v[106:107], v[100:101], v[126:127] op_sel_hi:[0,1]
	v_pk_mul_f32 v[108:109], v[100:101], v[120:121] op_sel_hi:[0,1]
	v_pk_mul_f32 v[110:111], v[100:101], v[128:129] op_sel_hi:[0,1]
	v_pk_mul_f32 v[112:113], v[100:101], v[122:123] op_sel_hi:[0,1]
	v_pk_mul_f32 v[114:115], v[100:101], v[130:131] op_sel_hi:[0,1]
	v_pk_mul_f32 v[116:117], v[100:101], v[124:125] op_sel_hi:[0,1]
	v_pk_mul_f32 v[100:101], v[0:1], v[102:103]
	v_pk_mul_f32 v[102:103], v[2:3], v[104:105]
	v_pk_mul_f32 v[104:105], v[4:5], v[106:107]
	v_pk_mul_f32 v[106:107], v[6:7], v[108:109]
	v_pk_mul_f32 v[108:109], v[8:9], v[110:111]
	v_pk_mul_f32 v[110:111], v[10:11], v[112:113]
	v_pk_mul_f32 v[112:113], v[12:13], v[114:115]
	v_pk_mul_f32 v[114:115], v[14:15], v[116:117]
	global_store_dwordx4 v[20:21], v[100:103], off offset:-2048 nt
	global_store_dwordx4 v[20:21], v[104:107], off offset:-1024 nt
	global_store_dwordx4 v[20:21], v[108:111], off nt
	global_store_dwordx4 v[20:21], v[112:115], off offset:1024 nt
	v_lshl_add_u64 v[20:21], v[20:21], 0, s[6:7]
	s_waitcnt vmcnt(16)
	v_mov_b32_e32 v176, v160
	v_mov_b32_e32 v177, v164
	v_mov_b32_e32 v164, v161
	v_mov_b32_e32 v160, v162
	v_mov_b32_e32 v161, v166
	v_mov_b32_e32 v166, v163
	v_mov_b32_e32 v162, v168
	v_mov_b32_e32 v163, v172
	v_mov_b32_e32 v172, v169
	v_mov_b32_e32 v168, v170
	v_mov_b32_e32 v169, v174
	v_mov_b32_e32 v174, v171
	v_pk_add_f32 v[164:165], v[176:177], v[164:165]
	v_pk_add_f32 v[160:161], v[160:161], v[166:167]
	v_pk_add_f32 v[162:163], v[162:163], v[172:173]
	v_pk_add_f32 v[166:167], v[168:169], v[174:175]
	v_pk_add_f32 v[160:161], v[164:165], v[160:161]
	v_pk_add_f32 v[162:163], v[162:163], v[166:167]
	v_lshlrev_b32_e32 v170, 16, v178
	v_pk_add_f32 v[160:161], v[160:161], v[162:163]
	v_and_b32_e32 v171, 0xffff0000, v178
	v_add_f32_e32 v160, v160, v161
	v_fmamk_f32 v160, v160, 0x3a800000, v16
	v_rsq_f32_e32 v160, v160
	v_lshlrev_b32_e32 v178, 16, v179
	v_and_b32_e32 v179, 0xffff0000, v179
	v_lshlrev_b32_e32 v186, 16, v180
	v_and_b32_e32 v187, 0xffff0000, v180
	v_lshlrev_b32_e32 v180, 16, v181
	v_and_b32_e32 v181, 0xffff0000, v181
	v_lshlrev_b32_e32 v188, 16, v182
	v_and_b32_e32 v189, 0xffff0000, v182
	v_lshlrev_b32_e32 v182, 16, v183
	v_and_b32_e32 v183, 0xffff0000, v183
	v_lshlrev_b32_e32 v190, 16, v184
	v_and_b32_e32 v191, 0xffff0000, v184
	v_lshlrev_b32_e32 v184, 16, v185
	v_and_b32_e32 v185, 0xffff0000, v185
	v_pk_mul_f32 v[162:163], v[160:161], v[170:171] op_sel_hi:[0,1]
	v_pk_mul_f32 v[164:165], v[160:161], v[178:179] op_sel_hi:[0,1]
	v_pk_mul_f32 v[166:167], v[160:161], v[186:187] op_sel_hi:[0,1]
	v_pk_mul_f32 v[168:169], v[160:161], v[180:181] op_sel_hi:[0,1]
	v_pk_mul_f32 v[170:171], v[160:161], v[188:189] op_sel_hi:[0,1]
	v_pk_mul_f32 v[172:173], v[160:161], v[182:183] op_sel_hi:[0,1]
	v_pk_mul_f32 v[174:175], v[160:161], v[190:191] op_sel_hi:[0,1]
	v_pk_mul_f32 v[176:177], v[160:161], v[184:185] op_sel_hi:[0,1]
	v_pk_mul_f32 v[160:161], v[0:1], v[162:163]
	v_pk_mul_f32 v[162:163], v[2:3], v[164:165]
	v_pk_mul_f32 v[164:165], v[4:5], v[166:167]
	v_pk_mul_f32 v[166:167], v[6:7], v[168:169]
	v_pk_mul_f32 v[168:169], v[8:9], v[170:171]
	v_pk_mul_f32 v[170:171], v[10:11], v[172:173]
	v_pk_mul_f32 v[172:173], v[12:13], v[174:175]
	v_pk_mul_f32 v[174:175], v[14:15], v[176:177]
	global_store_dwordx4 v[20:21], v[160:163], off offset:-2048 nt
	global_store_dwordx4 v[20:21], v[164:167], off offset:-1024 nt
	global_store_dwordx4 v[20:21], v[168:171], off nt
	global_store_dwordx4 v[20:21], v[172:175], off offset:1024 nt
	v_lshl_add_u64 v[20:21], v[20:21], 0, s[6:7]
	s_waitcnt vmcnt(12)
; __device__ __forceinline__ float bflo(unsigned u) { return __uint_as_float(u << 16); }
; __device__ __forceinline__ float bfhi(unsigned u) { return __uint_as_float(u & 0xffff0000u); }
; __device__ __forceinline__ void rms_row_final(const bf16* __restrict__ xrow, const float* __restrict__ srow, float* __restrict__ orow, const float* __restrict__ gain, int lane) {
;     const f32x4 s0 = *(const f32x4*)srow, s1 = *(const f32x4*)(srow + 4), s2 = *(const f32x4*)(srow + 8), s3 = *(const f32x4*)(srow + 12);
;     const float ss = (((s0[0] + s0[1]) + (s0[2] + s0[3])) + ((s1[0] + s1[1]) + (s1[2] + s1[3]))) + (((s2[0] + s2[1]) + (s2[2] + s2[3])) + ((s3[0] + s3[1]) + (s3[2] + s3[3])));
;     const float rstd = __builtin_amdgcn_rsqf(ss * (1.f / D) + 1e-6f);
;     const v2u* xr = (const v2u*)xrow + lane; const f32x4* gr = (const f32x4*)gain + lane; f32x4* o = (f32x4*)orow + lane;
; #pragma unroll
;     for (int j = 0; j < 4; ++j) { const v2u v = __builtin_nontemporal_load(xr + 64 * j); const f32x4 g4 = gr[64 * j];
;         const f32x4 r4 = {bflo(v.x) * rstd * g4[0], bfhi(v.x) * rstd * g4[1], bflo(v.y) * rstd * g4[2], bfhi(v.y) * rstd * g4[3]}; __builtin_nontemporal_store(r4, o + 64 * j); }
; }
; __global__ void __launch_bounds__(NTHREADS, 2) trunk_fwd(Args args) {
;     ...
;     if (IN(14)) for (int m = gw; m < M; m += NGW) rms_row_final(XB + (size_t)m * D, slots + (size_t)m * 16, out + (size_t)m * D, final_norm, lane);
	v_mov_b32_e32 v216, v200
	v_mov_b32_e32 v217, v204
	v_mov_b32_e32 v204, v201
	v_mov_b32_e32 v200, v202
	v_mov_b32_e32 v201, v206
	v_mov_b32_e32 v206, v203
	v_mov_b32_e32 v202, v208
	v_mov_b32_e32 v203, v212
	v_mov_b32_e32 v212, v209
	v_mov_b32_e32 v208, v210
	v_mov_b32_e32 v209, v214
	v_mov_b32_e32 v214, v211
	v_pk_add_f32 v[204:205], v[216:217], v[204:205]
	v_pk_add_f32 v[200:201], v[200:201], v[206:207]
	v_pk_add_f32 v[202:203], v[202:203], v[212:213]
	v_pk_add_f32 v[206:207], v[208:209], v[214:215]
	v_pk_add_f32 v[200:201], v[204:205], v[200:201]
	v_pk_add_f32 v[202:203], v[202:203], v[206:207]
	v_lshlrev_b32_e32 v210, 16, v218
	v_pk_add_f32 v[200:201], v[200:201], v[202:203]
	v_and_b32_e32 v211, 0xffff0000, v218
	v_add_f32_e32 v200, v200, v201
	v_fmamk_f32 v200, v200, 0x3a800000, v16
	v_rsq_f32_e32 v200, v200
	v_lshlrev_b32_e32 v218, 16, v219
	v_and_b32_e32 v219, 0xffff0000, v219
	v_lshlrev_b32_e32 v226, 16, v220
	v_and_b32_e32 v227, 0xffff0000, v220
	v_lshlrev_b32_e32 v220, 16, v221
	v_and_b32_e32 v221, 0xffff0000, v221
	v_lshlrev_b32_e32 v228, 16, v222
	v_and_b32_e32 v229, 0xffff0000, v222
	v_lshlrev_b32_e32 v222, 16, v223
	v_and_b32_e32 v223, 0xffff0000, v223
	v_lshlrev_b32_e32 v230, 16, v224
	v_and_b32_e32 v231, 0xffff0000, v224
	v_lshlrev_b32_e32 v224, 16, v225
	v_and_b32_e32 v225, 0xffff0000, v225
	v_pk_mul_f32 v[202:203], v[200:201], v[210:211] op_sel_hi:[0,1]
	v_pk_mul_f32 v[204:205], v[200:201], v[218:219] op_sel_hi:[0,1]
	v_pk_mul_f32 v[206:207], v[200:201], v[226:227] op_sel_hi:[0,1]
	v_pk_mul_f32 v[208:209], v[200:201], v[220:221] op_sel_hi:[0,1]
	v_pk_mul_f32 v[210:211], v[200:201], v[228:229] op_sel_hi:[0,1]
	v_pk_mul_f32 v[212:213], v[200:201], v[222:223] op_sel_hi:[0,1]
	v_pk_mul_f32 v[214:215], v[200:201], v[230:231] op_sel_hi:[0,1]
	v_pk_mul_f32 v[216:217], v[200:201], v[224:225] op_sel_hi:[0,1]
	v_pk_mul_f32 v[200:201], v[0:1], v[202:203]
	v_pk_mul_f32 v[202:203], v[2:3], v[204:205]
	v_pk_mul_f32 v[204:205], v[4:5], v[206:207]
	v_pk_mul_f32 v[206:207], v[6:7], v[208:209]
	v_pk_mul_f32 v[208:209], v[8:9], v[210:211]
	v_pk_mul_f32 v[210:211], v[10:11], v[212:213]
	v_pk_mul_f32 v[212:213], v[12:13], v[214:215]
	v_pk_mul_f32 v[214:215], v[14:15], v[216:217]
	global_store_dwordx4 v[20:21], v[200:203], off offset:-2048 nt
	global_store_dwordx4 v[20:21], v[204:207], off offset:-1024 nt
	global_store_dwordx4 v[20:21], v[208:211], off nt
	global_store_dwordx4 v[20:21], v[212:215], off offset:1024 nt
	v_lshl_add_u64 v[20:21], v[20:21], 0, s[6:7]
	s_cmp_lt_i32 s12, 0x8000
	s_cbranch_scc1 .Lp14_group
	s_branch .LBB0_1276
